# plus hyena ctx items: filter-tap accumulation loop with 8 steps of loads in flight
# speedup vs baseline: 1.0055x; 1.0055x over previous
; __device__ __forceinline__ void hyena_phase(const Params& P, int l, LAS unsigned char* lds) {
;     ...
;                     const float* wpf = w3 + ord * 2048 + c; const float* wpb = wpf + 1024;
;                     f32x4 af0 = {0.f, 0.f, 0.f, 0.f}, af1 = af0, ab0 = af0, ab1 = af0;
; #pragma unroll 4
;                     for (int j = 0; j < 64; ++j) { const float wf = wpf[(size_t)j * 4096], wb = wpb[(size_t)j * 4096];
;                         const f32x4 h0 = *(const f32x4*)(HC + j * 256 + tg * 8), h1 = *(const f32x4*)(HC + j * 256 + tg * 8 + 4);
;                         af0 += h0 * wf; af1 += h1 * wf; ab0 += h0 * wb; ab1 += h1 * wb; }
.LBB0_343:
	s_lshl_b64 s[22:23], s[86:87], 13
	v_mov_b32_e32 v50, 0
	s_xor_b64 s[20:21], s[10:11], -1
	v_lshl_add_u64 v[44:45], v[38:39], 0, s[22:23]
	s_mov_b64 s[22:23], 0
	v_mov_b64_e32 v[46:47], v[40:41]
	v_mov_b32_e32 v51, v50
	v_mov_b32_e32 v48, v50
	v_mov_b32_e32 v49, v50
	v_mov_b32_e32 v58, v50
	v_mov_b32_e32 v59, v50
	v_mov_b32_e32 v56, v50
	v_mov_b32_e32 v57, v50
	v_mov_b32_e32 v54, v50
	v_mov_b32_e32 v55, v50
	v_mov_b32_e32 v52, v50
	v_mov_b32_e32 v53, v50
	v_mov_b32_e32 v62, v50
	v_mov_b32_e32 v63, v50
	v_mov_b32_e32 v60, v50
	v_mov_b32_e32 v61, v50
	v_lshl_add_u64 v[104:105], v[44:45], 0, s[74:75]
	s_mov_b64 s[22:23], 0x4000
	global_load_dword v120, v[104:105], off offset:-4096
	global_load_dword v121, v[104:105], off
	global_load_dwordx4 v[116:119], v[46:47], off offset:-3072
	global_load_dwordx4 v[112:115], v[46:47], off offset:-3088
	v_lshl_add_u64 v[104:105], v[104:105], 0, s[22:23]
	global_load_dword v130, v[104:105], off offset:-4096
	global_load_dword v131, v[104:105], off
	global_load_dwordx4 v[126:129], v[46:47], off offset:-2048
	global_load_dwordx4 v[122:125], v[46:47], off offset:-2064
	v_lshl_add_u64 v[104:105], v[104:105], 0, s[22:23]
	global_load_dword v140, v[104:105], off offset:-4096
	global_load_dword v141, v[104:105], off
	global_load_dwordx4 v[136:139], v[46:47], off offset:-1024
	global_load_dwordx4 v[132:135], v[46:47], off offset:-1040
	v_lshl_add_u64 v[104:105], v[104:105], 0, s[22:23]
	global_load_dword v150, v[104:105], off offset:-4096
	global_load_dword v151, v[104:105], off
	global_load_dwordx4 v[146:149], v[46:47], off
	global_load_dwordx4 v[142:145], v[46:47], off offset:-16
	v_lshl_add_u64 v[104:105], v[104:105], 0, s[22:23]
	v_lshl_add_u64 v[46:47], v[46:47], 0, s[74:75]
	global_load_dword v160, v[104:105], off offset:-4096
	global_load_dword v161, v[104:105], off
	global_load_dwordx4 v[156:159], v[46:47], off offset:-3072
	global_load_dwordx4 v[152:155], v[46:47], off offset:-3088
	v_lshl_add_u64 v[104:105], v[104:105], 0, s[22:23]
	global_load_dword v170, v[104:105], off offset:-4096
	global_load_dword v171, v[104:105], off
	global_load_dwordx4 v[166:169], v[46:47], off offset:-2048
	global_load_dwordx4 v[162:165], v[46:47], off offset:-2064
	v_lshl_add_u64 v[104:105], v[104:105], 0, s[22:23]
	global_load_dword v180, v[104:105], off offset:-4096
	global_load_dword v181, v[104:105], off
	global_load_dwordx4 v[176:179], v[46:47], off offset:-1024
	global_load_dwordx4 v[172:175], v[46:47], off offset:-1040
	v_lshl_add_u64 v[104:105], v[104:105], 0, s[22:23]
	global_load_dword v190, v[104:105], off offset:-4096
	global_load_dword v191, v[104:105], off
	global_load_dwordx4 v[186:189], v[46:47], off
	global_load_dwordx4 v[182:185], v[46:47], off offset:-16
	v_lshl_add_u64 v[104:105], v[104:105], 0, s[22:23]
	v_lshl_add_u64 v[46:47], v[46:47], 0, s[74:75]
	s_mov_b32 vcc_lo, 0
.Lhyc_loop:
	s_waitcnt vmcnt(28)
	v_pk_fma_f32 v[62:63], v[112:113], v[120:121], v[62:63] op_sel_hi:[1,0,1]
	v_pk_fma_f32 v[60:61], v[114:115], v[120:121], v[60:61] op_sel_hi:[1,0,1]
	v_pk_fma_f32 v[54:55], v[116:117], v[120:121], v[54:55] op_sel_hi:[1,0,1]
	v_pk_fma_f32 v[52:53], v[118:119], v[120:121], v[52:53] op_sel_hi:[1,0,1]
	v_pk_fma_f32 v[58:59], v[112:113], v[120:121], v[58:59] op_sel:[0,1,0]
	v_pk_fma_f32 v[56:57], v[114:115], v[120:121], v[56:57] op_sel:[0,1,0]
	v_pk_fma_f32 v[50:51], v[116:117], v[120:121], v[50:51] op_sel:[0,1,0]
	v_pk_fma_f32 v[48:49], v[118:119], v[120:121], v[48:49] op_sel:[0,1,0]
	global_load_dword v120, v[104:105], off offset:-4096
	global_load_dword v121, v[104:105], off
	global_load_dwordx4 v[116:119], v[46:47], off offset:-3072
	global_load_dwordx4 v[112:115], v[46:47], off offset:-3088
	v_lshl_add_u64 v[104:105], v[104:105], 0, s[22:23]
	s_waitcnt vmcnt(28)
	v_pk_fma_f32 v[62:63], v[122:123], v[130:131], v[62:63] op_sel_hi:[1,0,1]
	v_pk_fma_f32 v[60:61], v[124:125], v[130:131], v[60:61] op_sel_hi:[1,0,1]
	v_pk_fma_f32 v[54:55], v[126:127], v[130:131], v[54:55] op_sel_hi:[1,0,1]
	v_pk_fma_f32 v[52:53], v[128:129], v[130:131], v[52:53] op_sel_hi:[1,0,1]
	v_pk_fma_f32 v[58:59], v[122:123], v[130:131], v[58:59] op_sel:[0,1,0]
	v_pk_fma_f32 v[56:57], v[124:125], v[130:131], v[56:57] op_sel:[0,1,0]
	v_pk_fma_f32 v[50:51], v[126:127], v[130:131], v[50:51] op_sel:[0,1,0]
	v_pk_fma_f32 v[48:49], v[128:129], v[130:131], v[48:49] op_sel:[0,1,0]
	global_load_dword v130, v[104:105], off offset:-4096
	global_load_dword v131, v[104:105], off
	global_load_dwordx4 v[126:129], v[46:47], off offset:-2048
	global_load_dwordx4 v[122:125], v[46:47], off offset:-2064
	v_lshl_add_u64 v[104:105], v[104:105], 0, s[22:23]
	s_waitcnt vmcnt(28)
	v_pk_fma_f32 v[62:63], v[132:133], v[140:141], v[62:63] op_sel_hi:[1,0,1]
	v_pk_fma_f32 v[60:61], v[134:135], v[140:141], v[60:61] op_sel_hi:[1,0,1]
	v_pk_fma_f32 v[54:55], v[136:137], v[140:141], v[54:55] op_sel_hi:[1,0,1]
	v_pk_fma_f32 v[52:53], v[138:139], v[140:141], v[52:53] op_sel_hi:[1,0,1]
	v_pk_fma_f32 v[58:59], v[132:133], v[140:141], v[58:59] op_sel:[0,1,0]
	v_pk_fma_f32 v[56:57], v[134:135], v[140:141], v[56:57] op_sel:[0,1,0]
	v_pk_fma_f32 v[50:51], v[136:137], v[140:141], v[50:51] op_sel:[0,1,0]
	v_pk_fma_f32 v[48:49], v[138:139], v[140:141], v[48:49] op_sel:[0,1,0]
	global_load_dword v140, v[104:105], off offset:-4096
	global_load_dword v141, v[104:105], off
	global_load_dwordx4 v[136:139], v[46:47], off offset:-1024
	global_load_dwordx4 v[132:135], v[46:47], off offset:-1040
	v_lshl_add_u64 v[104:105], v[104:105], 0, s[22:23]
	s_waitcnt vmcnt(28)
; __device__ __forceinline__ void hyena_phase(const Params& P, int l, LAS unsigned char* lds) {
;     ...
;                     for (int j = 0; j < 64; ++j) { const float wf = wpf[(size_t)j * 4096], wb = wpb[(size_t)j * 4096];
;                         const f32x4 h0 = *(const f32x4*)(HC + j * 256 + tg * 8), h1 = *(const f32x4*)(HC + j * 256 + tg * 8 + 4);
;                         af0 += h0 * wf; af1 += h1 * wf; ab0 += h0 * wb; ab1 += h1 * wb; }
	v_pk_fma_f32 v[62:63], v[142:143], v[150:151], v[62:63] op_sel_hi:[1,0,1]
	v_pk_fma_f32 v[60:61], v[144:145], v[150:151], v[60:61] op_sel_hi:[1,0,1]
	v_pk_fma_f32 v[54:55], v[146:147], v[150:151], v[54:55] op_sel_hi:[1,0,1]
	v_pk_fma_f32 v[52:53], v[148:149], v[150:151], v[52:53] op_sel_hi:[1,0,1]
	v_pk_fma_f32 v[58:59], v[142:143], v[150:151], v[58:59] op_sel:[0,1,0]
	v_pk_fma_f32 v[56:57], v[144:145], v[150:151], v[56:57] op_sel:[0,1,0]
	v_pk_fma_f32 v[50:51], v[146:147], v[150:151], v[50:51] op_sel:[0,1,0]
	v_pk_fma_f32 v[48:49], v[148:149], v[150:151], v[48:49] op_sel:[0,1,0]
	global_load_dword v150, v[104:105], off offset:-4096
	global_load_dword v151, v[104:105], off
	global_load_dwordx4 v[146:149], v[46:47], off
	global_load_dwordx4 v[142:145], v[46:47], off offset:-16
	v_lshl_add_u64 v[104:105], v[104:105], 0, s[22:23]
	v_lshl_add_u64 v[46:47], v[46:47], 0, s[74:75]
	s_waitcnt vmcnt(28)
	v_pk_fma_f32 v[62:63], v[152:153], v[160:161], v[62:63] op_sel_hi:[1,0,1]
	v_pk_fma_f32 v[60:61], v[154:155], v[160:161], v[60:61] op_sel_hi:[1,0,1]
	v_pk_fma_f32 v[54:55], v[156:157], v[160:161], v[54:55] op_sel_hi:[1,0,1]
	v_pk_fma_f32 v[52:53], v[158:159], v[160:161], v[52:53] op_sel_hi:[1,0,1]
	v_pk_fma_f32 v[58:59], v[152:153], v[160:161], v[58:59] op_sel:[0,1,0]
	v_pk_fma_f32 v[56:57], v[154:155], v[160:161], v[56:57] op_sel:[0,1,0]
	v_pk_fma_f32 v[50:51], v[156:157], v[160:161], v[50:51] op_sel:[0,1,0]
	v_pk_fma_f32 v[48:49], v[158:159], v[160:161], v[48:49] op_sel:[0,1,0]
	global_load_dword v160, v[104:105], off offset:-4096
	global_load_dword v161, v[104:105], off
	global_load_dwordx4 v[156:159], v[46:47], off offset:-3072
	global_load_dwordx4 v[152:155], v[46:47], off offset:-3088
	v_lshl_add_u64 v[104:105], v[104:105], 0, s[22:23]
	s_waitcnt vmcnt(28)
	v_pk_fma_f32 v[62:63], v[162:163], v[170:171], v[62:63] op_sel_hi:[1,0,1]
	v_pk_fma_f32 v[60:61], v[164:165], v[170:171], v[60:61] op_sel_hi:[1,0,1]
	v_pk_fma_f32 v[54:55], v[166:167], v[170:171], v[54:55] op_sel_hi:[1,0,1]
	v_pk_fma_f32 v[52:53], v[168:169], v[170:171], v[52:53] op_sel_hi:[1,0,1]
	v_pk_fma_f32 v[58:59], v[162:163], v[170:171], v[58:59] op_sel:[0,1,0]
	v_pk_fma_f32 v[56:57], v[164:165], v[170:171], v[56:57] op_sel:[0,1,0]
	v_pk_fma_f32 v[50:51], v[166:167], v[170:171], v[50:51] op_sel:[0,1,0]
	v_pk_fma_f32 v[48:49], v[168:169], v[170:171], v[48:49] op_sel:[0,1,0]
	global_load_dword v170, v[104:105], off offset:-4096
	global_load_dword v171, v[104:105], off
	global_load_dwordx4 v[166:169], v[46:47], off offset:-2048
	global_load_dwordx4 v[162:165], v[46:47], off offset:-2064
	v_lshl_add_u64 v[104:105], v[104:105], 0, s[22:23]
	s_waitcnt vmcnt(28)
	v_pk_fma_f32 v[62:63], v[172:173], v[180:181], v[62:63] op_sel_hi:[1,0,1]
	v_pk_fma_f32 v[60:61], v[174:175], v[180:181], v[60:61] op_sel_hi:[1,0,1]
	v_pk_fma_f32 v[54:55], v[176:177], v[180:181], v[54:55] op_sel_hi:[1,0,1]
	v_pk_fma_f32 v[52:53], v[178:179], v[180:181], v[52:53] op_sel_hi:[1,0,1]
	v_pk_fma_f32 v[58:59], v[172:173], v[180:181], v[58:59] op_sel:[0,1,0]
	v_pk_fma_f32 v[56:57], v[174:175], v[180:181], v[56:57] op_sel:[0,1,0]
	v_pk_fma_f32 v[50:51], v[176:177], v[180:181], v[50:51] op_sel:[0,1,0]
	v_pk_fma_f32 v[48:49], v[178:179], v[180:181], v[48:49] op_sel:[0,1,0]
	global_load_dword v180, v[104:105], off offset:-4096
	global_load_dword v181, v[104:105], off
	global_load_dwordx4 v[176:179], v[46:47], off offset:-1024
	global_load_dwordx4 v[172:175], v[46:47], off offset:-1040
	v_lshl_add_u64 v[104:105], v[104:105], 0, s[22:23]
	s_waitcnt vmcnt(28)
	v_pk_fma_f32 v[62:63], v[182:183], v[190:191], v[62:63] op_sel_hi:[1,0,1]
	v_pk_fma_f32 v[60:61], v[184:185], v[190:191], v[60:61] op_sel_hi:[1,0,1]
	v_pk_fma_f32 v[54:55], v[186:187], v[190:191], v[54:55] op_sel_hi:[1,0,1]
	v_pk_fma_f32 v[52:53], v[188:189], v[190:191], v[52:53] op_sel_hi:[1,0,1]
	v_pk_fma_f32 v[58:59], v[182:183], v[190:191], v[58:59] op_sel:[0,1,0]
	v_pk_fma_f32 v[56:57], v[184:185], v[190:191], v[56:57] op_sel:[0,1,0]
	v_pk_fma_f32 v[50:51], v[186:187], v[190:191], v[50:51] op_sel:[0,1,0]
	v_pk_fma_f32 v[48:49], v[188:189], v[190:191], v[48:49] op_sel:[0,1,0]
	global_load_dword v190, v[104:105], off offset:-4096
	global_load_dword v191, v[104:105], off
	global_load_dwordx4 v[186:189], v[46:47], off
	global_load_dwordx4 v[182:185], v[46:47], off offset:-16
	v_lshl_add_u64 v[104:105], v[104:105], 0, s[22:23]
	v_lshl_add_u64 v[46:47], v[46:47], 0, s[74:75]
	s_add_i32 vcc_lo, vcc_lo, 1
	s_cmp_lg_u32 vcc_lo, 7
	s_cbranch_scc1 .Lhyc_loop
; __device__ __forceinline__ void hyena_phase(const Params& P, int l, LAS unsigned char* lds) {
;     ...
;                     for (int j = 0; j < 64; ++j) { const float wf = wpf[(size_t)j * 4096], wb = wpb[(size_t)j * 4096];
;                         const f32x4 h0 = *(const f32x4*)(HC + j * 256 + tg * 8), h1 = *(const f32x4*)(HC + j * 256 + tg * 8 + 4);
;                         af0 += h0 * wf; af1 += h1 * wf; ab0 += h0 * wb; ab1 += h1 * wb; }
; #pragma unroll
;                     for (int e = 0; e < 8; ++e) { const int tau = tg * 8 + e; const float win = __expf(-((float)tau * (1.f / 255.f)) * dl);
;                         filt[(255 + tau) * 16 + ch] = win * (e < 4 ? af0[e & 3] : af1[e & 3]);
;                         if (tau >= 1) filt[(255 - tau) * 16 + ch] = win * (e < 4 ? ab0[e & 3] : ab1[e & 3]); }
	s_waitcnt vmcnt(28)
	v_pk_fma_f32 v[62:63], v[112:113], v[120:121], v[62:63] op_sel_hi:[1,0,1]
	v_pk_fma_f32 v[60:61], v[114:115], v[120:121], v[60:61] op_sel_hi:[1,0,1]
	v_pk_fma_f32 v[54:55], v[116:117], v[120:121], v[54:55] op_sel_hi:[1,0,1]
	v_pk_fma_f32 v[52:53], v[118:119], v[120:121], v[52:53] op_sel_hi:[1,0,1]
	v_pk_fma_f32 v[58:59], v[112:113], v[120:121], v[58:59] op_sel:[0,1,0]
	v_pk_fma_f32 v[56:57], v[114:115], v[120:121], v[56:57] op_sel:[0,1,0]
	v_pk_fma_f32 v[50:51], v[116:117], v[120:121], v[50:51] op_sel:[0,1,0]
	v_pk_fma_f32 v[48:49], v[118:119], v[120:121], v[48:49] op_sel:[0,1,0]
	s_waitcnt vmcnt(24)
	v_pk_fma_f32 v[62:63], v[122:123], v[130:131], v[62:63] op_sel_hi:[1,0,1]
	v_pk_fma_f32 v[60:61], v[124:125], v[130:131], v[60:61] op_sel_hi:[1,0,1]
	v_pk_fma_f32 v[54:55], v[126:127], v[130:131], v[54:55] op_sel_hi:[1,0,1]
	v_pk_fma_f32 v[52:53], v[128:129], v[130:131], v[52:53] op_sel_hi:[1,0,1]
	v_pk_fma_f32 v[58:59], v[122:123], v[130:131], v[58:59] op_sel:[0,1,0]
	v_pk_fma_f32 v[56:57], v[124:125], v[130:131], v[56:57] op_sel:[0,1,0]
	v_pk_fma_f32 v[50:51], v[126:127], v[130:131], v[50:51] op_sel:[0,1,0]
	v_pk_fma_f32 v[48:49], v[128:129], v[130:131], v[48:49] op_sel:[0,1,0]
	s_waitcnt vmcnt(20)
	v_pk_fma_f32 v[62:63], v[132:133], v[140:141], v[62:63] op_sel_hi:[1,0,1]
	v_pk_fma_f32 v[60:61], v[134:135], v[140:141], v[60:61] op_sel_hi:[1,0,1]
	v_pk_fma_f32 v[54:55], v[136:137], v[140:141], v[54:55] op_sel_hi:[1,0,1]
	v_pk_fma_f32 v[52:53], v[138:139], v[140:141], v[52:53] op_sel_hi:[1,0,1]
	v_pk_fma_f32 v[58:59], v[132:133], v[140:141], v[58:59] op_sel:[0,1,0]
	v_pk_fma_f32 v[56:57], v[134:135], v[140:141], v[56:57] op_sel:[0,1,0]
	v_pk_fma_f32 v[50:51], v[136:137], v[140:141], v[50:51] op_sel:[0,1,0]
	v_pk_fma_f32 v[48:49], v[138:139], v[140:141], v[48:49] op_sel:[0,1,0]
	s_waitcnt vmcnt(16)
	v_pk_fma_f32 v[62:63], v[142:143], v[150:151], v[62:63] op_sel_hi:[1,0,1]
	v_pk_fma_f32 v[60:61], v[144:145], v[150:151], v[60:61] op_sel_hi:[1,0,1]
	v_pk_fma_f32 v[54:55], v[146:147], v[150:151], v[54:55] op_sel_hi:[1,0,1]
	v_pk_fma_f32 v[52:53], v[148:149], v[150:151], v[52:53] op_sel_hi:[1,0,1]
	v_pk_fma_f32 v[58:59], v[142:143], v[150:151], v[58:59] op_sel:[0,1,0]
	v_pk_fma_f32 v[56:57], v[144:145], v[150:151], v[56:57] op_sel:[0,1,0]
	v_pk_fma_f32 v[50:51], v[146:147], v[150:151], v[50:51] op_sel:[0,1,0]
	v_pk_fma_f32 v[48:49], v[148:149], v[150:151], v[48:49] op_sel:[0,1,0]
	s_waitcnt vmcnt(12)
	v_pk_fma_f32 v[62:63], v[152:153], v[160:161], v[62:63] op_sel_hi:[1,0,1]
	v_pk_fma_f32 v[60:61], v[154:155], v[160:161], v[60:61] op_sel_hi:[1,0,1]
	v_pk_fma_f32 v[54:55], v[156:157], v[160:161], v[54:55] op_sel_hi:[1,0,1]
	v_pk_fma_f32 v[52:53], v[158:159], v[160:161], v[52:53] op_sel_hi:[1,0,1]
	v_pk_fma_f32 v[58:59], v[152:153], v[160:161], v[58:59] op_sel:[0,1,0]
	v_pk_fma_f32 v[56:57], v[154:155], v[160:161], v[56:57] op_sel:[0,1,0]
	v_pk_fma_f32 v[50:51], v[156:157], v[160:161], v[50:51] op_sel:[0,1,0]
	v_pk_fma_f32 v[48:49], v[158:159], v[160:161], v[48:49] op_sel:[0,1,0]
	s_waitcnt vmcnt(8)
	v_pk_fma_f32 v[62:63], v[162:163], v[170:171], v[62:63] op_sel_hi:[1,0,1]
	v_pk_fma_f32 v[60:61], v[164:165], v[170:171], v[60:61] op_sel_hi:[1,0,1]
	v_pk_fma_f32 v[54:55], v[166:167], v[170:171], v[54:55] op_sel_hi:[1,0,1]
	v_pk_fma_f32 v[52:53], v[168:169], v[170:171], v[52:53] op_sel_hi:[1,0,1]
	v_pk_fma_f32 v[58:59], v[162:163], v[170:171], v[58:59] op_sel:[0,1,0]
	v_pk_fma_f32 v[56:57], v[164:165], v[170:171], v[56:57] op_sel:[0,1,0]
	v_pk_fma_f32 v[50:51], v[166:167], v[170:171], v[50:51] op_sel:[0,1,0]
	v_pk_fma_f32 v[48:49], v[168:169], v[170:171], v[48:49] op_sel:[0,1,0]
	s_waitcnt vmcnt(4)
	v_pk_fma_f32 v[62:63], v[172:173], v[180:181], v[62:63] op_sel_hi:[1,0,1]
	v_pk_fma_f32 v[60:61], v[174:175], v[180:181], v[60:61] op_sel_hi:[1,0,1]
	v_pk_fma_f32 v[54:55], v[176:177], v[180:181], v[54:55] op_sel_hi:[1,0,1]
	v_pk_fma_f32 v[52:53], v[178:179], v[180:181], v[52:53] op_sel_hi:[1,0,1]
	v_pk_fma_f32 v[58:59], v[172:173], v[180:181], v[58:59] op_sel:[0,1,0]
	v_pk_fma_f32 v[56:57], v[174:175], v[180:181], v[56:57] op_sel:[0,1,0]
	v_pk_fma_f32 v[50:51], v[176:177], v[180:181], v[50:51] op_sel:[0,1,0]
	v_pk_fma_f32 v[48:49], v[178:179], v[180:181], v[48:49] op_sel:[0,1,0]
	s_waitcnt vmcnt(0)
	v_pk_fma_f32 v[62:63], v[182:183], v[190:191], v[62:63] op_sel_hi:[1,0,1]
	v_pk_fma_f32 v[60:61], v[184:185], v[190:191], v[60:61] op_sel_hi:[1,0,1]
	v_pk_fma_f32 v[54:55], v[186:187], v[190:191], v[54:55] op_sel_hi:[1,0,1]
	v_pk_fma_f32 v[52:53], v[188:189], v[190:191], v[52:53] op_sel_hi:[1,0,1]
	v_pk_fma_f32 v[58:59], v[182:183], v[190:191], v[58:59] op_sel:[0,1,0]
	v_pk_fma_f32 v[56:57], v[184:185], v[190:191], v[56:57] op_sel:[0,1,0]
	v_pk_fma_f32 v[50:51], v[186:187], v[190:191], v[50:51] op_sel:[0,1,0]
	v_pk_fma_f32 v[48:49], v[188:189], v[190:191], v[48:49] op_sel:[0,1,0]
	s_mov_b32 s54, 0xd000
	s_mov_b64 s[22:23], 0x100000
	v_mul_f32_e32 v2, v1, v62
	ds_write_b32 v65, v2 offset:16320
	s_and_saveexec_b64 s[22:23], s[4:5]
	v_mul_f32_e32 v2, v1, v58
	ds_write_b32 v66, v2 offset:16320
	s_or_b64 exec, exec, s[22:23]
	v_mul_f32_e32 v2, v67, v63
	ds_write_b32 v69, v2 offset:16320
	v_mul_f32_e32 v2, v71, v60
	s_and_saveexec_b64 s[22:23], s[8:9]
	s_xor_b64 s[22:23], exec, s[22:23]
	ds_write_b32 v73, v2 offset:16320
	s_andn2_saveexec_b64 s[22:23], s[22:23]
	s_cbranch_execz .LBB0_351
	v_mul_f32_e32 v43, v67, v59
	ds_write_b32 v70, v43 offset:16320
	ds_write_b32 v73, v2 offset:16320
	v_mul_f32_e32 v2, v71, v56
	ds_write_b32 v74, v2 offset:16320
